# P1 epilogue: 72 redundant is_q selects removed (the scale register is already 1.0 for the other column groups)
# baseline (speedup 1.0000x reference)
; __device__ __forceinline__ unsigned cvt_pk_bf16(float lo, float hi) { const f32x2_t v = {lo, hi}; const bf16x2_t b = __builtin_convertvector(v, bf16x2_t); return __builtin_bit_cast(unsigned, b); }
;     __device__ __forceinline__ void operator()(f32x4 (&acc)[2][2][4][2], const Unit& u, int wr, int wc, int fr, int fq) const {
;     ...
;                 bf16_t* rowp = U + (size_t)r * LDU + g64 * 64 + 8 * fq;
; #pragma unroll
;                 for (int bj = 0; bj < 2; ++bj) {
;                     f32x4 v0 = v[bj][0], v1 = v[bj][1]; if (is_q) { v0 = v0 * post; v1 = v1 * post; }
;                     u32x4 w; w.x = cvt_pk_bf16(v0[0], v0[1]); w.y = cvt_pk_bf16(v0[2], v0[3]); w.z = cvt_pk_bf16(v1[0], v1[1]); w.w = cvt_pk_bf16(v1[2], v1[3]);
;                     __builtin_nontemporal_store(w, (u32x4*)(rowp + 32 * bj));
;                 }
.LBB0_165:
	v_mov_b64_e32 v[130:131], s[82:83]
	s_ashr_i32 s37, s36, 31
	v_mad_i64_i32 v[130:131], s[0:1], v132, s92, v[130:131]
	v_cndmask_b32_e64 v186, 1.0, v197, s[6:7]
	v_lshl_add_u64 v[130:131], s[36:37], 1, v[130:131]
	v_lshl_add_u64 v[134:135], v[130:131], 0, v[172:173]
	v_pk_mul_f32 v[130:131], v[186:187], v[146:147] op_sel_hi:[0,1]
	v_pk_mul_f32 v[132:133], v[186:187], v[148:149] op_sel_hi:[0,1]
	v_pk_mul_f32 v[136:137], v[186:187], v[150:151] op_sel_hi:[0,1]
	v_pk_mul_f32 v[138:139], v[186:187], v[152:153] op_sel_hi:[0,1]
	v_cvt_pk_bf16_f32 v130, v130, v131
	v_cvt_pk_bf16_f32 v131, v132, v133
	v_cvt_pk_bf16_f32 v132, v136, v137
	v_cvt_pk_bf16_f32 v133, v138, v139
	global_store_dwordx4 v[134:135], v[130:133], off
	v_pk_mul_f32 v[136:137], v[186:187], v[158:159] op_sel_hi:[0,1]
	v_pk_mul_f32 v[138:139], v[186:187], v[160:161] op_sel_hi:[0,1]
	v_pk_mul_f32 v[130:131], v[186:187], v[154:155] op_sel_hi:[0,1]
	v_pk_mul_f32 v[132:133], v[186:187], v[156:157] op_sel_hi:[0,1]
	v_cvt_pk_bf16_f32 v130, v130, v131
	v_cvt_pk_bf16_f32 v131, v132, v133
	v_cvt_pk_bf16_f32 v132, v136, v137
	v_cvt_pk_bf16_f32 v133, v138, v139
	global_store_dwordx4 v[134:135], v[130:133], off offset:64
	s_andn2_b64 vcc, exec, s[86:87]
	s_mov_b64 s[0:1], -1
	v_cndmask_b32_e64 v130, 0, 1, s[86:87]
	v_cmp_ne_u32_e64 s[12:13], 1, v130
	s_cbranch_vccnz .LBB0_183
	s_cmp_lt_i32 s15, 8
	s_cbranch_scc1 .LBB0_174
	s_cmp_gt_i32 s15, 9
	s_cselect_b64 s[10:11], -1, 0
	s_cbranch_execz .LBB0_175
	s_branch .LBB0_176

; __device__ __forceinline__ unsigned cvt_pk_bf16(float lo, float hi) { const f32x2_t v = {lo, hi}; const bf16x2_t b = __builtin_convertvector(v, bf16x2_t); return __builtin_bit_cast(unsigned, b); }
;     __device__ __forceinline__ void operator()(f32x4 (&acc)[2][2][4][2], const Unit& u, int wr, int wc, int fr, int fq) const {
;     ...
;                 bf16_t* rowp = U + (size_t)r * LDU + g64 * 64 + 8 * fq;
; #pragma unroll
;                 for (int bj = 0; bj < 2; ++bj) {
;                     f32x4 v0 = v[bj][0], v1 = v[bj][1]; if (is_q) { v0 = v0 * post; v1 = v1 * post; }
;                     u32x4 w; w.x = cvt_pk_bf16(v0[0], v0[1]); w.y = cvt_pk_bf16(v0[2], v0[3]); w.z = cvt_pk_bf16(v1[0], v1[1]); w.w = cvt_pk_bf16(v1[2], v1[3]);
;                     __builtin_nontemporal_store(w, (u32x4*)(rowp + 32 * bj));
;                 }
.LBB0_195:
	v_mov_b64_e32 v[114:115], s[82:83]
	v_mad_i64_i32 v[114:115], s[0:1], v116, s92, v[114:115]
	v_mov_b32_e32 v187, v186
	v_lshl_add_u64 v[114:115], s[36:37], 1, v[114:115]
	v_mov_b32_e32 v120, v186
	v_mov_b32_e32 v121, v186
	v_lshl_add_u64 v[118:119], v[114:115], 0, v[172:173]
	v_pk_mul_f32 v[114:115], v[120:121], v[132:133]
	v_pk_mul_f32 v[116:117], v[186:187], v[130:131]
	v_pk_mul_f32 v[122:123], v[120:121], v[136:137]
	v_pk_mul_f32 v[124:125], v[186:187], v[134:135]
	v_cndmask_b32_e64 v126, v132, v114, s[6:7]
	v_cndmask_b32_e64 v114, v131, v117, s[6:7]
	v_cndmask_b32_e64 v117, v137, v123, s[6:7]
	v_cndmask_b32_e64 v123, v135, v125, s[6:7]
	v_cvt_pk_bf16_f32 v114, v116, v114
	v_cvt_pk_bf16_f32 v115, v126, v115
	v_cvt_pk_bf16_f32 v116, v124, v123
	v_cvt_pk_bf16_f32 v117, v122, v117
	global_store_dwordx4 v[118:119], v[114:117], off
	v_pk_mul_f32 v[122:123], v[186:187], v[142:143]
	s_and_b64 vcc, exec, s[12:13]
	v_pk_mul_f32 v[114:115], v[120:121], v[140:141]
	v_pk_mul_f32 v[116:117], v[186:187], v[138:139]
	v_pk_mul_f32 v[120:121], v[120:121], v[144:145]
	v_cndmask_b32_e64 v124, v140, v114, s[6:7]
	v_cndmask_b32_e64 v114, v139, v117, s[6:7]
	v_cndmask_b32_e64 v117, v145, v121, s[6:7]
	v_cndmask_b32_e64 v121, v143, v123, s[6:7]
	v_cvt_pk_bf16_f32 v114, v116, v114
	v_cvt_pk_bf16_f32 v115, v124, v115
	v_cvt_pk_bf16_f32 v116, v122, v121
	v_cvt_pk_bf16_f32 v117, v120, v117
	s_mov_b64 s[0:1], -1
	global_store_dwordx4 v[118:119], v[114:117], off offset:64
	s_cbranch_vccnz .LBB0_198
	s_cmp_lt_i32 s15, 8
	s_cbranch_scc1 .LBB0_206
	s_cmp_gt_i32 s15, 9
	s_cselect_b64 s[86:87], -1, 0
	s_cbranch_execz .LBB0_207
	s_branch .LBB0_208

; __device__ __forceinline__ unsigned cvt_pk_bf16(float lo, float hi) { const f32x2_t v = {lo, hi}; const bf16x2_t b = __builtin_convertvector(v, bf16x2_t); return __builtin_bit_cast(unsigned, b); }
;     __device__ __forceinline__ void operator()(f32x4 (&acc)[2][2][4][2], const Unit& u, int wr, int wc, int fr, int fq) const {
;     ...
;                 bf16_t* rowp = U + (size_t)r * LDU + g64 * 64 + 8 * fq;
; #pragma unroll
;                 for (int bj = 0; bj < 2; ++bj) {
;                     f32x4 v0 = v[bj][0], v1 = v[bj][1]; if (is_q) { v0 = v0 * post; v1 = v1 * post; }
;                     u32x4 w; w.x = cvt_pk_bf16(v0[0], v0[1]); w.y = cvt_pk_bf16(v0[2], v0[3]); w.z = cvt_pk_bf16(v1[0], v1[1]); w.w = cvt_pk_bf16(v1[2], v1[3]);
;                     __builtin_nontemporal_store(w, (u32x4*)(rowp + 32 * bj));
;                 }
.LBB0_225:
	v_mov_b64_e32 v[98:99], s[82:83]
	v_mad_i64_i32 v[98:99], s[0:1], v100, s92, v[98:99]
	v_lshl_add_u64 v[98:99], s[36:37], 1, v[98:99]
	v_mov_b32_e32 v104, v186
	v_mov_b32_e32 v105, v186
	v_lshl_add_u64 v[102:103], v[98:99], 0, v[172:173]
	v_pk_mul_f32 v[98:99], v[104:105], v[116:117]
	v_pk_mul_f32 v[100:101], v[186:187], v[114:115]
	v_pk_mul_f32 v[106:107], v[104:105], v[120:121]
	v_pk_mul_f32 v[108:109], v[186:187], v[118:119]
	v_cndmask_b32_e64 v110, v116, v98, s[6:7]
	v_cndmask_b32_e64 v98, v115, v101, s[6:7]
	v_cndmask_b32_e64 v101, v121, v107, s[6:7]
	v_cndmask_b32_e64 v107, v119, v109, s[6:7]
	v_cvt_pk_bf16_f32 v98, v100, v98
	v_cvt_pk_bf16_f32 v99, v110, v99
	v_cvt_pk_bf16_f32 v100, v108, v107
	v_cvt_pk_bf16_f32 v101, v106, v101
	global_store_dwordx4 v[102:103], v[98:101], off
	v_pk_mul_f32 v[106:107], v[186:187], v[126:127]
	s_and_b64 vcc, exec, s[12:13]
	v_pk_mul_f32 v[98:99], v[104:105], v[124:125]
	v_pk_mul_f32 v[100:101], v[186:187], v[122:123]
	v_pk_mul_f32 v[104:105], v[104:105], v[128:129]
	v_cndmask_b32_e64 v108, v124, v98, s[6:7]
	v_cndmask_b32_e64 v98, v123, v101, s[6:7]
	v_cndmask_b32_e64 v101, v129, v105, s[6:7]
	v_cndmask_b32_e64 v105, v127, v107, s[6:7]
	v_cvt_pk_bf16_f32 v98, v100, v98
	v_cvt_pk_bf16_f32 v99, v108, v99
	v_cvt_pk_bf16_f32 v100, v106, v105
	v_cvt_pk_bf16_f32 v101, v104, v101
	s_mov_b64 s[0:1], -1
	global_store_dwordx4 v[102:103], v[98:101], off offset:64
	s_cbranch_vccnz .LBB0_228
	s_cmp_lt_i32 s15, 8
	s_cbranch_scc1 .LBB0_236
	s_cmp_gt_i32 s15, 9
	s_cselect_b64 s[86:87], -1, 0
	s_cbranch_execz .LBB0_237
	s_branch .LBB0_238

; __device__ __forceinline__ unsigned cvt_pk_bf16(float lo, float hi) { const f32x2_t v = {lo, hi}; const bf16x2_t b = __builtin_convertvector(v, bf16x2_t); return __builtin_bit_cast(unsigned, b); }
;     __device__ __forceinline__ void operator()(f32x4 (&acc)[2][2][4][2], const Unit& u, int wr, int wc, int fr, int fq) const {
;     ...
;                 bf16_t* rowp = U + (size_t)r * LDU + g64 * 64 + 8 * fq;
; #pragma unroll
;                 for (int bj = 0; bj < 2; ++bj) {
;                     f32x4 v0 = v[bj][0], v1 = v[bj][1]; if (is_q) { v0 = v0 * post; v1 = v1 * post; }
;                     u32x4 w; w.x = cvt_pk_bf16(v0[0], v0[1]); w.y = cvt_pk_bf16(v0[2], v0[3]); w.z = cvt_pk_bf16(v1[0], v1[1]); w.w = cvt_pk_bf16(v1[2], v1[3]);
;                     __builtin_nontemporal_store(w, (u32x4*)(rowp + 32 * bj));
;                 }
.LBB0_255:
	v_mov_b64_e32 v[82:83], s[82:83]
	v_mad_i64_i32 v[82:83], s[0:1], v84, s92, v[82:83]
	v_lshl_add_u64 v[82:83], s[36:37], 1, v[82:83]
	v_mov_b32_e32 v88, v186
	v_mov_b32_e32 v89, v186
	v_lshl_add_u64 v[86:87], v[82:83], 0, v[172:173]
	v_pk_mul_f32 v[82:83], v[88:89], v[100:101]
	v_pk_mul_f32 v[84:85], v[186:187], v[98:99]
	v_pk_mul_f32 v[90:91], v[88:89], v[104:105]
	v_pk_mul_f32 v[92:93], v[186:187], v[102:103]
	v_cndmask_b32_e64 v94, v100, v82, s[6:7]
	v_cndmask_b32_e64 v82, v99, v85, s[6:7]
	v_cndmask_b32_e64 v85, v105, v91, s[6:7]
	v_cndmask_b32_e64 v91, v103, v93, s[6:7]
	v_cvt_pk_bf16_f32 v82, v84, v82
	v_cvt_pk_bf16_f32 v83, v94, v83
	v_cvt_pk_bf16_f32 v84, v92, v91
	v_cvt_pk_bf16_f32 v85, v90, v85
	global_store_dwordx4 v[86:87], v[82:85], off
	v_pk_mul_f32 v[90:91], v[186:187], v[110:111]
	s_and_b64 vcc, exec, s[12:13]
	v_pk_mul_f32 v[82:83], v[88:89], v[108:109]
	v_pk_mul_f32 v[84:85], v[186:187], v[106:107]
	v_pk_mul_f32 v[88:89], v[88:89], v[112:113]
	v_cndmask_b32_e64 v92, v108, v82, s[6:7]
	v_cndmask_b32_e64 v82, v107, v85, s[6:7]
	v_cndmask_b32_e64 v85, v113, v89, s[6:7]
	v_cndmask_b32_e64 v89, v111, v91, s[6:7]
	v_cvt_pk_bf16_f32 v82, v84, v82
	v_cvt_pk_bf16_f32 v83, v92, v83
	v_cvt_pk_bf16_f32 v84, v90, v89
	v_cvt_pk_bf16_f32 v85, v88, v85
	s_mov_b64 s[0:1], -1
	global_store_dwordx4 v[86:87], v[82:85], off offset:64
	s_cbranch_vccnz .LBB0_273
	s_cmp_lt_i32 s15, 8
	s_cbranch_scc1 .LBB0_264
	s_cmp_gt_i32 s15, 9
	s_cselect_b64 s[86:87], -1, 0
	s_cbranch_execz .LBB0_265
	s_branch .LBB0_266

; __device__ __forceinline__ unsigned cvt_pk_bf16(float lo, float hi) { const f32x2_t v = {lo, hi}; const bf16x2_t b = __builtin_convertvector(v, bf16x2_t); return __builtin_bit_cast(unsigned, b); }
;     __device__ __forceinline__ void operator()(f32x4 (&acc)[2][2][4][2], const Unit& u, int wr, int wc, int fr, int fq) const {
;     ...
;                 bf16_t* rowp = U + (size_t)r * LDU + g64 * 64 + 8 * fq;
; #pragma unroll
;                 for (int bj = 0; bj < 2; ++bj) {
;                     f32x4 v0 = v[bj][0], v1 = v[bj][1]; if (is_q) { v0 = v0 * post; v1 = v1 * post; }
;                     u32x4 w; w.x = cvt_pk_bf16(v0[0], v0[1]); w.y = cvt_pk_bf16(v0[2], v0[3]); w.z = cvt_pk_bf16(v1[0], v1[1]); w.w = cvt_pk_bf16(v1[2], v1[3]);
;                     __builtin_nontemporal_store(w, (u32x4*)(rowp + 32 * bj));
;                 }
.LBB0_285:
	v_mov_b64_e32 v[66:67], s[82:83]
	v_mad_i64_i32 v[66:67], s[0:1], v68, s92, v[66:67]
	v_lshl_add_u64 v[66:67], s[36:37], 1, v[66:67]
	v_mov_b32_e32 v72, v186
	v_mov_b32_e32 v73, v186
	v_lshl_add_u64 v[70:71], v[66:67], 0, v[172:173]
	v_pk_mul_f32 v[66:67], v[72:73], v[84:85]
	v_pk_mul_f32 v[68:69], v[186:187], v[82:83]
	v_pk_mul_f32 v[74:75], v[72:73], v[88:89]
	v_pk_mul_f32 v[76:77], v[186:187], v[86:87]
	v_cndmask_b32_e64 v78, v84, v66, s[6:7]
	v_cndmask_b32_e64 v66, v83, v69, s[6:7]
	v_cndmask_b32_e64 v69, v89, v75, s[6:7]
	v_cndmask_b32_e64 v75, v87, v77, s[6:7]
	v_cvt_pk_bf16_f32 v66, v68, v66
	v_cvt_pk_bf16_f32 v67, v78, v67
	v_cvt_pk_bf16_f32 v68, v76, v75
	v_cvt_pk_bf16_f32 v69, v74, v69
	global_store_dwordx4 v[70:71], v[66:69], off
	v_pk_mul_f32 v[74:75], v[186:187], v[94:95]
	s_and_b64 vcc, exec, s[12:13]
	v_pk_mul_f32 v[66:67], v[72:73], v[92:93]
	v_pk_mul_f32 v[68:69], v[186:187], v[90:91]
	v_pk_mul_f32 v[72:73], v[72:73], v[96:97]
	v_cndmask_b32_e64 v76, v92, v66, s[6:7]
	v_cndmask_b32_e64 v66, v91, v69, s[6:7]
	v_cndmask_b32_e64 v69, v97, v73, s[6:7]
	v_cndmask_b32_e64 v73, v95, v75, s[6:7]
	v_cvt_pk_bf16_f32 v66, v68, v66
	v_cvt_pk_bf16_f32 v67, v76, v67
	v_cvt_pk_bf16_f32 v68, v74, v73
	v_cvt_pk_bf16_f32 v69, v72, v69
	s_mov_b64 s[0:1], -1
	global_store_dwordx4 v[70:71], v[66:69], off offset:64
	s_cbranch_vccnz .LBB0_288
	s_cmp_lt_i32 s15, 8
	s_cbranch_scc1 .LBB0_296
	s_cmp_gt_i32 s15, 9
	s_cselect_b64 s[86:87], -1, 0
	s_cbranch_execz .LBB0_297
	s_branch .LBB0_298

; __device__ __forceinline__ unsigned cvt_pk_bf16(float lo, float hi) { const f32x2_t v = {lo, hi}; const bf16x2_t b = __builtin_convertvector(v, bf16x2_t); return __builtin_bit_cast(unsigned, b); }
;     __device__ __forceinline__ void operator()(f32x4 (&acc)[2][2][4][2], const Unit& u, int wr, int wc, int fr, int fq) const {
;     ...
;                 bf16_t* rowp = U + (size_t)r * LDU + g64 * 64 + 8 * fq;
; #pragma unroll
;                 for (int bj = 0; bj < 2; ++bj) {
;                     f32x4 v0 = v[bj][0], v1 = v[bj][1]; if (is_q) { v0 = v0 * post; v1 = v1 * post; }
;                     u32x4 w; w.x = cvt_pk_bf16(v0[0], v0[1]); w.y = cvt_pk_bf16(v0[2], v0[3]); w.z = cvt_pk_bf16(v1[0], v1[1]); w.w = cvt_pk_bf16(v1[2], v1[3]);
;                     __builtin_nontemporal_store(w, (u32x4*)(rowp + 32 * bj));
;                 }
.LBB0_315:
	v_mov_b64_e32 v[50:51], s[82:83]
	v_mad_i64_i32 v[50:51], s[0:1], v52, s92, v[50:51]
	v_lshl_add_u64 v[50:51], s[36:37], 1, v[50:51]
	v_mov_b32_e32 v56, v186
	v_mov_b32_e32 v57, v186
	v_lshl_add_u64 v[54:55], v[50:51], 0, v[172:173]
	v_pk_mul_f32 v[50:51], v[56:57], v[68:69]
	v_pk_mul_f32 v[52:53], v[186:187], v[66:67]
	v_pk_mul_f32 v[58:59], v[56:57], v[72:73]
	v_pk_mul_f32 v[60:61], v[186:187], v[70:71]
	v_cndmask_b32_e64 v62, v68, v50, s[6:7]
	v_cndmask_b32_e64 v50, v67, v53, s[6:7]
	v_cndmask_b32_e64 v53, v73, v59, s[6:7]
	v_cndmask_b32_e64 v59, v71, v61, s[6:7]
	v_cvt_pk_bf16_f32 v50, v52, v50
	v_cvt_pk_bf16_f32 v51, v62, v51
	v_cvt_pk_bf16_f32 v52, v60, v59
	v_cvt_pk_bf16_f32 v53, v58, v53
	global_store_dwordx4 v[54:55], v[50:53], off
	v_pk_mul_f32 v[58:59], v[186:187], v[78:79]
	s_and_b64 vcc, exec, s[12:13]
	v_pk_mul_f32 v[50:51], v[56:57], v[76:77]
	v_pk_mul_f32 v[52:53], v[186:187], v[74:75]
	v_pk_mul_f32 v[56:57], v[56:57], v[80:81]
	v_cndmask_b32_e64 v60, v76, v50, s[6:7]
	v_cndmask_b32_e64 v50, v75, v53, s[6:7]
	v_cndmask_b32_e64 v53, v81, v57, s[6:7]
	v_cndmask_b32_e64 v57, v79, v59, s[6:7]
	v_cvt_pk_bf16_f32 v50, v52, v50
	v_cvt_pk_bf16_f32 v51, v60, v51
	v_cvt_pk_bf16_f32 v52, v58, v57
	v_cvt_pk_bf16_f32 v53, v56, v53
	s_mov_b64 s[0:1], -1
	global_store_dwordx4 v[54:55], v[50:53], off offset:64
	s_cbranch_vccnz .LBB0_318
	s_cmp_lt_i32 s15, 8
	s_cbranch_scc1 .LBB0_326
	s_cmp_gt_i32 s15, 9
	s_cselect_b64 s[86:87], -1, 0
	s_cbranch_execz .LBB0_327
	s_branch .LBB0_328

; __device__ __forceinline__ unsigned cvt_pk_bf16(float lo, float hi) { const f32x2_t v = {lo, hi}; const bf16x2_t b = __builtin_convertvector(v, bf16x2_t); return __builtin_bit_cast(unsigned, b); }
;     __device__ __forceinline__ void operator()(f32x4 (&acc)[2][2][4][2], const Unit& u, int wr, int wc, int fr, int fq) const {
;     ...
;                 bf16_t* rowp = U + (size_t)r * LDU + g64 * 64 + 8 * fq;
; #pragma unroll
;                 for (int bj = 0; bj < 2; ++bj) {
;                     f32x4 v0 = v[bj][0], v1 = v[bj][1]; if (is_q) { v0 = v0 * post; v1 = v1 * post; }
;                     u32x4 w; w.x = cvt_pk_bf16(v0[0], v0[1]); w.y = cvt_pk_bf16(v0[2], v0[3]); w.z = cvt_pk_bf16(v1[0], v1[1]); w.w = cvt_pk_bf16(v1[2], v1[3]);
;                     __builtin_nontemporal_store(w, (u32x4*)(rowp + 32 * bj));
;                 }
.LBB0_345:
	v_mov_b64_e32 v[18:19], s[82:83]
	v_mad_i64_i32 v[18:19], s[0:1], v20, s92, v[18:19]
	v_lshl_add_u64 v[18:19], s[36:37], 1, v[18:19]
	v_mov_b32_e32 v24, v186
	v_mov_b32_e32 v25, v186
	v_lshl_add_u64 v[22:23], v[18:19], 0, v[172:173]
	v_pk_mul_f32 v[18:19], v[24:25], v[52:53]
	v_pk_mul_f32 v[20:21], v[186:187], v[50:51]
	v_pk_mul_f32 v[34:35], v[24:25], v[56:57]
	v_pk_mul_f32 v[36:37], v[186:187], v[54:55]
	v_cndmask_b32_e64 v38, v52, v18, s[6:7]
	v_cndmask_b32_e64 v18, v51, v21, s[6:7]
	v_cndmask_b32_e64 v21, v57, v35, s[6:7]
	v_cndmask_b32_e64 v35, v55, v37, s[6:7]
	v_cvt_pk_bf16_f32 v18, v20, v18
	v_cvt_pk_bf16_f32 v19, v38, v19
	v_cvt_pk_bf16_f32 v20, v36, v35
	v_cvt_pk_bf16_f32 v21, v34, v21
	global_store_dwordx4 v[22:23], v[18:21], off
	v_pk_mul_f32 v[34:35], v[186:187], v[62:63]
	s_and_b64 vcc, exec, s[12:13]
	v_pk_mul_f32 v[18:19], v[24:25], v[60:61]
	v_pk_mul_f32 v[20:21], v[186:187], v[58:59]
	v_pk_mul_f32 v[24:25], v[24:25], v[64:65]
	v_cndmask_b32_e64 v36, v60, v18, s[6:7]
	v_cndmask_b32_e64 v18, v59, v21, s[6:7]
	v_cndmask_b32_e64 v21, v65, v25, s[6:7]
	v_cndmask_b32_e64 v25, v63, v35, s[6:7]
	v_cvt_pk_bf16_f32 v18, v20, v18
	v_cvt_pk_bf16_f32 v19, v36, v19
	v_cvt_pk_bf16_f32 v20, v34, v25
	v_cvt_pk_bf16_f32 v21, v24, v21
	s_mov_b64 s[0:1], -1
	global_store_dwordx4 v[22:23], v[18:21], off offset:64
	s_cbranch_vccnz .LBB0_348
	s_cmp_lt_i32 s15, 8
	s_cbranch_scc1 .LBB0_356
	s_cmp_gt_i32 s15, 9
	s_cselect_b64 s[12:13], -1, 0
	s_cbranch_execz .LBB0_357
	s_branch .LBB0_358

; __device__ __forceinline__ unsigned cvt_pk_bf16(float lo, float hi) { const f32x2_t v = {lo, hi}; const bf16x2_t b = __builtin_convertvector(v, bf16x2_t); return __builtin_bit_cast(unsigned, b); }
; #define PG8_BAR __builtin_amdgcn_s_barrier()
; template <class Epi, int AC0, int BC0, int NT0, int AC1, int BC1, int NT1>
; __device__ __forceinline__ void gemm_phase(LAS unsigned char* lds, const Gemm g, const StaticOrder& S, const Epi& E, int tid) {
;     ...
;         if (!has_next) break;
;         if (!(Epi::KEEP0 && cur.seg == 0)) {
; #pragma unroll
;             for (int a = 0; a < 2; ++a)
; #pragma unroll
;                 for (int b = 0; b < 2; ++b)
; #pragma unroll
;                     for (int m = 0; m < 4; ++m)
; #pragma unroll
;                         for (int n = 0; n < 2; ++n) acc[a][b][m][n] = (f32x4){0.f, 0.f, 0.f, 0.f};
;         }
;         cur = nxt; cA = nA; cB = nB; ++ui;
;         if (wr == 1) PG8_BAR;
;     __device__ __forceinline__ void operator()(f32x4 (&acc)[2][2][4][2], const Unit& u, int wr, int wc, int fr, int fq) const {
;     ...
;                 bf16_t* rowp = U + (size_t)r * LDU + g64 * 64 + 8 * fq;
; #pragma unroll
;                 for (int bj = 0; bj < 2; ++bj) {
;                     f32x4 v0 = v[bj][0], v1 = v[bj][1]; if (is_q) { v0 = v0 * post; v1 = v1 * post; }
;                     u32x4 w; w.x = cvt_pk_bf16(v0[0], v0[1]); w.y = cvt_pk_bf16(v0[2], v0[3]); w.z = cvt_pk_bf16(v1[0], v1[1]); w.w = cvt_pk_bf16(v1[2], v1[3]);
;                     __builtin_nontemporal_store(w, (u32x4*)(rowp + 32 * bj));
;                 }
.LBB0_375:
	v_mov_b64_e32 v[2:3], s[82:83]
	v_mad_i64_i32 v[2:3], s[0:1], v4, s92, v[2:3]
	v_lshl_add_u64 v[2:3], s[36:37], 1, v[2:3]
	v_mov_b32_e32 v8, v186
	v_mov_b32_e32 v9, v186
	v_lshl_add_u64 v[6:7], v[2:3], 0, v[172:173]
	v_pk_mul_f32 v[2:3], v[8:9], v[20:21]
	v_pk_mul_f32 v[4:5], v[186:187], v[18:19]
	v_pk_mul_f32 v[10:11], v[8:9], v[24:25]
	v_pk_mul_f32 v[12:13], v[186:187], v[22:23]
	v_cndmask_b32_e64 v14, v20, v2, s[6:7]
	v_cndmask_b32_e64 v2, v19, v5, s[6:7]
	v_cndmask_b32_e64 v5, v25, v11, s[6:7]
	v_cndmask_b32_e64 v11, v23, v13, s[6:7]
	v_cvt_pk_bf16_f32 v2, v4, v2
	v_cvt_pk_bf16_f32 v3, v14, v3
	v_cvt_pk_bf16_f32 v4, v12, v11
	v_cvt_pk_bf16_f32 v5, v10, v5
	global_store_dwordx4 v[6:7], v[2:5], off
	v_pk_mul_f32 v[10:11], v[186:187], v[38:39]
	s_andn2_b64 vcc, exec, s[4:5]
	v_pk_mul_f32 v[2:3], v[8:9], v[36:37]
	v_pk_mul_f32 v[4:5], v[186:187], v[34:35]
	v_pk_mul_f32 v[8:9], v[8:9], v[40:41]
	v_cndmask_b32_e64 v12, v36, v2, s[6:7]
	v_cndmask_b32_e64 v2, v35, v5, s[6:7]
	v_cndmask_b32_e64 v5, v41, v9, s[6:7]
	v_cndmask_b32_e64 v9, v39, v11, s[6:7]
	v_cvt_pk_bf16_f32 v2, v4, v2
	v_cvt_pk_bf16_f32 v3, v12, v3
	v_cvt_pk_bf16_f32 v4, v10, v9
	v_cvt_pk_bf16_f32 v5, v8, v5
	s_mov_b64 s[0:1], -1
	global_store_dwordx4 v[6:7], v[2:5], off offset:64
	s_cbranch_vccnz .LBB0_116
	v_readlane_b32 s0, v254, 15
	v_readlane_b32 s1, v254, 16
	s_andn2_b64 vcc, exec, s[0:1]
	s_cbranch_vccnz .LBB0_115
	s_barrier
	s_branch .LBB0_115
